# v11 + m3 order swap (s5 pass-b first on blocks >=256) to overlap latency-bound s5 with attention of co-resident block
# baseline (speedup 1.0000x reference)
; #define LAS __attribute__((address_space(3)))
; __global__ void __launch_bounds__(256, 2) mega(Params p, int ph_lo, int ph_hi) {
;     ...
;     __shared__ u32x4 xbw;
;     if (threadIdx.x == 0) xbw = (u32x4){0u, 0u, 0u, 0u};
;     __syncthreads();
;     XcdBarrier xb = xcd_barrier_post((unsigned*)(p.ws + OFF_BAR), (volatile LAS unsigned*)&xbw);
.LBB0_2:
	s_or_b64 exec, exec, s[4:5]
	s_waitcnt lgkmcnt(0)
	s_barrier
	s_lshr_b32 s3, s2, 8
	s_and_b32 s3, s3, 1
	v_mov_b32_e32 v2, s3
	v_mov_b32_e32 v3, 0x12008
	s_mov_b64 s[4:5], exec
	v_cmp_eq_u32_e32 vcc, 0, v133
	s_and_b64 exec, exec, vcc
	ds_write_b32 v3, v2
	s_mov_b64 exec, s[4:5]
	s_waitcnt lgkmcnt(0)
	s_barrier
	s_mov_b32 m0, 0
	s_add_u32 s4, s96, 0x15e18000
	s_getreg_b32 s3, hwreg(HW_REG_XCC_ID, 0, 4)
	s_addc_u32 s5, s97, 0
	s_and_b32 s10, s3, 15
	s_mov_b64 s[6:7], exec
	v_readlane_b32 s8, v223, 8
	v_readlane_b32 s9, v223, 9
	s_and_b64 s[8:9], s[6:7], s[8:9]
	s_mov_b64 exec, s[8:9]
	s_cbranch_execz .LBB0_5
	s_mov_b64 s[8:9], exec
	v_mbcnt_lo_u32_b32 v1, s8, 0
	v_mbcnt_hi_u32_b32 v1, s9, v1
	v_cmp_eq_u32_e32 vcc, 0, v1
	s_and_b64 s[12:13], exec, vcc
	s_mov_b64 exec, s[12:13]
	s_cbranch_execz .LBB0_5
	s_lshl_b32 s3, s10, 8
	s_bcnt1_i32_b64 s8, s[8:9]
	v_mov_b32_e32 v1, s3
	v_mov_b32_e32 v2, s8
	global_atomic_add v1, v2, s[4:5] offset:1024

; DEVI void phase_m3(const Params& p, int l, unsigned char* smem) {
;     const int G = gridDim.x, bid = blockIdx.x;
;     if ((G & 7) == 0) {
;         const int x = bid & 7, bg = x & 3, nb = G >> 3, lb = (bid >> 3) + nb * (x >> 2);
;         for (int pi = lb; pi < 128; pi += 2 * nb) {
;             attn_item(p, bg, (255 - pi) * 32, smem);
;             attn_item(p, bg, pi * 32, smem);
;         }
;     } else {
;         for (int item = bid; item < 1024; item += G) attn_item(p, item & 3, (item >> 2) * 32, smem);
.LBB0_400:
	s_cmp_lg_u32 m0, 0
	s_cbranch_scc1 .Lm3_attn
	ds_read_b32 v0, v143 offset:8
	s_waitcnt lgkmcnt(0)
	v_readfirstlane_b32 s0, v0
	s_nop 0
	s_cmp_eq_u32 s0, 0
	s_cbranch_scc1 .Lm3_attn
	s_mov_b32 m0, 1
	s_branch .LBB0_704

; DEVI int wave_() { return __builtin_amdgcn_readfirstlane(tid_() >> 6); }
; DEVI void phase_m3(const Params& p, int l, unsigned char* smem) {
;     ...
;         for (int item = bid; item < 1024; item += G) attn_item(p, item & 3, (item >> 2) * 32, smem);
;     }
;     for (int i = bid; i < 1024; i += G) {
;         const int wv = wave_();
;         int wi = i * 4 + wv;
;         if (i >= 512) { const int k = (wi >> 4) & 127; wi = (wi & ~(127 << 4)) | ((127 - k) << 4); }
;         __syncthreads();
;         s5_pass_b(p, l, wi, smem + wv * 16384);
;     }
.LBB0_704:
	s_cmp_eq_u32 m0, 2
	s_cbranch_scc0 .Lm3_s5go
	s_mov_b32 m0, 0
	s_branch .LBB0_720

; DEVI bf16_t f2bf(float f) { return (bf16_t)(pk_bf16(f, 0.f) & 0xffffu); }
; DEVI float bf2f(bf16_t v) { return __uint_as_float((unsigned)v << 16); }
; DEVI void s5_pass_b(const Params& p, int l, int witem, unsigned char* wlraw) {
;     ...
; #pragma unroll 4
;         for (int tt = 0; tt < 32; ++tt) {
;             const float xr = bf2f(Hs[tt * 136 + lane]), xi = bf2f(Hs[tt * 136 + 64 + lane]);
;             const float nr = a4.x * hr - a4.y * hi + xr, ni = a4.x * hi + a4.y * hr + xi;
;             hr = nr; hi = ni;
;             Hs[tt * 136 + lane] = f2bf(hr);
;             Hs[tt * 136 + 64 + lane] = f2bf(hi);
;         }
.LBB0_717:
	v_add_u32_e32 v68, s26, v66
	ds_read_u16 v54, v68
	ds_read_u16 v55, v68 offset:128
	v_pk_mul_f32 v[52:53], v[62:63], v[72:73] op_sel:[0,1]
	s_addk_i32 s26, 0x440
	v_pk_fma_f32 v[56:57], v[2:3], v[72:73], v[52:53] neg_lo:[0,0,1] neg_hi:[0,0,1]
	v_pk_fma_f32 v[52:53], v[2:3], v[72:73], v[52:53] op_sel_hi:[1,0,1]
	s_waitcnt lgkmcnt(0)
	v_lshlrev_b32_e32 v55, 16, v55
	v_lshlrev_b32_e32 v54, 16, v54
	v_mov_b32_e32 v57, v53
	v_pk_add_f32 v[52:53], v[56:57], v[54:55]
	s_cmpk_eq_i32 s26, 0x3200
	v_cvt_pk_bf16_f32 v54, v52, s0
	ds_write_b16 v68, v54
	v_cvt_pk_bf16_f32 v54, v53, s0
	ds_write_b16 v68, v54 offset:128
	ds_read_u16 v56, v68 offset:272
	ds_read_u16 v57, v68 offset:400
	v_pk_mul_f32 v[54:55], v[62:63], v[52:53] op_sel:[0,1]
	s_waitcnt lgkmcnt(1)
	v_lshlrev_b32_e32 v56, 16, v56
	v_pk_fma_f32 v[58:59], v[2:3], v[52:53], v[54:55] neg_lo:[0,0,1] neg_hi:[0,0,1]
	v_pk_fma_f32 v[52:53], v[2:3], v[52:53], v[54:55] op_sel_hi:[1,0,1]
	s_waitcnt lgkmcnt(0)
	v_lshlrev_b32_e32 v57, 16, v57
	v_mov_b32_e32 v59, v53
	v_pk_add_f32 v[52:53], v[58:59], v[56:57]
	s_nop 0
	v_cvt_pk_bf16_f32 v54, v52, s0
	ds_write_b16 v68, v54 offset:272
	v_cvt_pk_bf16_f32 v54, v53, s0
	ds_write_b16 v68, v54 offset:400
	ds_read_u16 v56, v68 offset:544
	ds_read_u16 v57, v68 offset:672
	v_pk_mul_f32 v[54:55], v[62:63], v[52:53] op_sel:[0,1]
	s_waitcnt lgkmcnt(1)
	v_lshlrev_b32_e32 v56, 16, v56
	v_pk_fma_f32 v[58:59], v[2:3], v[52:53], v[54:55] neg_lo:[0,0,1] neg_hi:[0,0,1]
	v_pk_fma_f32 v[52:53], v[2:3], v[52:53], v[54:55] op_sel_hi:[1,0,1]
	s_waitcnt lgkmcnt(0)
	v_lshlrev_b32_e32 v57, 16, v57
	v_mov_b32_e32 v59, v53
	v_pk_add_f32 v[52:53], v[58:59], v[56:57]
	s_nop 0
	v_cvt_pk_bf16_f32 v54, v52, s0
	ds_write_b16 v68, v54 offset:544
	v_cvt_pk_bf16_f32 v54, v53, s0
	ds_write_b16 v68, v54 offset:672
	ds_read_u16 v56, v68 offset:816
	ds_read_u16 v57, v68 offset:944
	v_pk_mul_f32 v[54:55], v[62:63], v[52:53] op_sel:[0,1]
	s_waitcnt lgkmcnt(1)
	v_lshlrev_b32_e32 v56, 16, v56
	v_pk_fma_f32 v[58:59], v[2:3], v[52:53], v[54:55] neg_lo:[0,0,1] neg_hi:[0,0,1]
	v_pk_fma_f32 v[52:53], v[2:3], v[52:53], v[54:55] op_sel_hi:[1,0,1]
	s_waitcnt lgkmcnt(0)
	v_lshlrev_b32_e32 v57, 16, v57
	v_mov_b32_e32 v59, v53
	v_pk_add_f32 v[72:73], v[58:59], v[56:57]
	s_nop 0
	v_cvt_pk_bf16_f32 v52, v72, s0
	ds_write_b16 v68, v52 offset:816
	v_cvt_pk_bf16_f32 v52, v73, s0
	ds_write_b16 v68, v52 offset:944
	s_cbranch_scc0 .LBB0_717
; DEVI int wave_() { return __builtin_amdgcn_readfirstlane(tid_() >> 6); }
; DEVI bf16_t f2bf(float f) { return (bf16_t)(pk_bf16(f, 0.f) & 0xffffu); }
; DEVI f32x4 mfma16(bf16x8 a, bf16x8 b, f32x4 c) { return __builtin_amdgcn_mfma_f32_16x16x32_bf16(a, b, c, 0, 0, 0); }
; DEVI void s5_pass_b(const Params& p, int l, int witem, unsigned char* wlraw) {
;     ...
;         f32x4 y[2];
; #pragma unroll
;         for (int mt = 0; mt < 2; ++mt) {
;             y[mt] = (f32x4){0.f, 0.f, 0.f, 0.f};
; #pragma unroll
;             for (int ks = 0; ks < 4; ++ks) {
;                 const bf16x8 hf = *(const bf16x8*)(Hs + (mt * 16 + l16) * 136 + ks * 32 + quad * 8);
;                 y[mt] = mfma16(hf, cf[ks], y[mt]);
;             }
;         }
; #pragma unroll
;         for (int mt = 0; mt < 2; ++mt)
; #pragma unroll
;             for (int r = 0; r < 4; ++r) {
;                 const int t = half * 32 + mt * 16 + quad * 4 + r;
;                 const float yy = y[mt][r] + dsk * us[t * 16 + l16];
;                 yg[(size_t)(tok0 + t) * 256 + G * 16 + l16] = f2bf(gelu_tanh(yy));
;             }
;         __builtin_amdgcn_fence(__ATOMIC_RELEASE, "wavefront");
;         __builtin_amdgcn_wave_barrier();
;         __builtin_amdgcn_fence(__ATOMIC_ACQUIRE, "wavefront");
;     }
; DEVI void phase_m3(const Params& p, int l, unsigned char* smem) {
;     ...
;     for (int i = bid; i < 1024; i += G) {
;         const int wv = wave_();
;         int wi = i * 4 + wv;
;         if (i >= 512) { const int k = (wi >> 4) & 127; wi = (wi & ~(127 << 4)) | ((127 - k) << 4); }
;         __syncthreads();
;         s5_pass_b(p, l, wi, smem + wv * 16384);
;     }
	ds_read_b128 v[52:55], v67 offset:4096
	ds_read_b128 v[56:59], v67 offset:4160
	s_mov_b64 s[26:27], 0
	s_and_b64 vcc, exec, s[24:25]
	s_waitcnt lgkmcnt(1)
	v_mfma_f32_16x16x32_bf16 v[52:55], v[52:55], v[36:39], 0
	ds_read_b128 v[68:71], v67 offset:8512
	s_waitcnt lgkmcnt(1)
	v_mfma_f32_16x16x32_bf16 v[52:55], v[56:59], v[40:43], v[52:55]
	ds_read_b128 v[56:59], v67 offset:4224
	s_waitcnt lgkmcnt(0)
	v_mfma_f32_16x16x32_bf16 v[52:55], v[56:59], v[44:47], v[52:55]
	ds_read_b128 v[56:59], v67 offset:4288
	s_waitcnt lgkmcnt(0)
	v_mfma_f32_16x16x32_bf16 v[56:59], v[56:59], v[48:51], v[52:55]
	s_nop 4
	ds_read_b128 v[52:55], v67 offset:8448
	s_waitcnt lgkmcnt(0)
	v_mfma_f32_16x16x32_bf16 v[52:55], v[52:55], v[36:39], 0
	v_mfma_f32_16x16x32_bf16 v[52:55], v[68:71], v[40:43], v[52:55]
	ds_read_b128 v[68:71], v67 offset:8576
	s_waitcnt lgkmcnt(0)
	v_mfma_f32_16x16x32_bf16 v[52:55], v[68:71], v[44:47], v[52:55]
	ds_read_b128 v[68:71], v67 offset:8640
	s_waitcnt lgkmcnt(0)
	v_mfma_f32_16x16x32_bf16 v[52:55], v[68:71], v[48:51], v[52:55]
	v_or_b32_e32 v68, s22, v65
	v_lshl_add_u32 v69, v68, 6, v0
	ds_read_b32 v69, v69
	v_or_b32_e32 v70, s40, v68
	v_ashrrev_i32_e32 v71, 31, v70
	v_lshlrev_b64 v[70:71], 9, v[70:71]
	v_lshl_add_u64 v[70:71], v[60:61], 0, v[70:71]
	s_waitcnt lgkmcnt(0)
	v_fma_f32 v56, v64, v69, v56
	v_mul_f32_e32 v69, 0x3d372713, v56
	v_mul_f32_e32 v69, v56, v69
	v_fma_f32 v69, v56, v69, v56
	v_mul_f32_e32 v69, 0x3f4c422a, v69
	v_mul_f32_e32 v69, 0x4038aa3b, v69
	v_exp_f32_e32 v69, v69
	v_mul_f32_e32 v56, 0.5, v56
	s_mov_b32 s22, 32
	v_add_f32_e32 v69, 1.0, v69
	v_rcp_f32_e32 v69, v69
	s_nop 0
	v_fma_f32 v69, v69, -2.0, 1.0
	v_add_f32_e32 v69, 1.0, v69
	v_mul_f32_e32 v56, v56, v69
	v_cvt_pk_bf16_f32 v56, v56, s0
	global_store_short v[70:71], v56, off
	v_or_b32_e32 v56, 1, v68
	v_lshl_add_u32 v69, v56, 6, v0
	ds_read_b32 v69, v69
	v_or_b32_e32 v56, s40, v56
	s_waitcnt lgkmcnt(0)
	v_fma_f32 v57, v64, v69, v57
	v_mul_f32_e32 v69, 0x3d372713, v57
	v_mul_f32_e32 v69, v57, v69
	v_fma_f32 v69, v57, v69, v57
	v_mul_f32_e32 v69, 0x3f4c422a, v69
	v_mul_f32_e32 v69, 0x4038aa3b, v69
	v_exp_f32_e32 v69, v69
	v_mul_f32_e32 v57, 0.5, v57
	v_add_f32_e32 v69, 1.0, v69
	v_rcp_f32_e32 v69, v69
	s_nop 0
	v_fma_f32 v69, v69, -2.0, 1.0
	v_add_f32_e32 v69, 1.0, v69
	v_mul_f32_e32 v57, v57, v69
	v_cvt_pk_bf16_f32 v69, v57, s0
	v_ashrrev_i32_e32 v57, 31, v56
	v_lshlrev_b64 v[56:57], 9, v[56:57]
	v_lshl_add_u64 v[56:57], v[60:61], 0, v[56:57]
	global_store_short v[56:57], v69, off
	v_or_b32_e32 v56, 2, v68
	v_lshl_add_u32 v57, v56, 6, v0
	ds_read_b32 v57, v57
	v_or_b32_e32 v56, s40, v56
	s_waitcnt lgkmcnt(0)
	v_fma_f32 v57, v64, v57, v58
	v_mul_f32_e32 v58, 0x3d372713, v57
	v_mul_f32_e32 v58, v57, v58
	v_fma_f32 v58, v57, v58, v57
	v_mul_f32_e32 v58, 0x3f4c422a, v58
	v_mul_f32_e32 v58, 0x4038aa3b, v58
	v_exp_f32_e32 v58, v58
	v_mul_f32_e32 v57, 0.5, v57
	v_add_f32_e32 v58, 1.0, v58
	v_rcp_f32_e32 v58, v58
	s_nop 0
	v_fma_f32 v58, v58, -2.0, 1.0
	v_add_f32_e32 v58, 1.0, v58
	v_mul_f32_e32 v57, v57, v58
	v_cvt_pk_bf16_f32 v58, v57, s0
	v_ashrrev_i32_e32 v57, 31, v56
	v_lshlrev_b64 v[56:57], 9, v[56:57]
	v_lshl_add_u64 v[56:57], v[60:61], 0, v[56:57]
	global_store_short v[56:57], v58, off
	v_or_b32_e32 v56, 3, v68
	v_lshl_add_u32 v57, v56, 6, v0
	ds_read_b32 v57, v57
	v_or_b32_e32 v56, s40, v56
	s_waitcnt lgkmcnt(0)
	v_fmac_f32_e32 v59, v64, v57
	v_mul_f32_e32 v57, 0x3d372713, v59
	v_mul_f32_e32 v57, v59, v57
	v_fma_f32 v57, v59, v57, v59
	v_mul_f32_e32 v57, 0x3f4c422a, v57
	v_mul_f32_e32 v57, 0x4038aa3b, v57
	v_exp_f32_e32 v57, v57
	v_mul_f32_e32 v58, 0.5, v59
	v_add_f32_e32 v57, 1.0, v57
	v_rcp_f32_e32 v57, v57
	s_nop 0
	v_fma_f32 v57, v57, -2.0, 1.0
	v_add_f32_e32 v57, 1.0, v57
	v_mul_f32_e32 v57, v58, v57
	v_cvt_pk_bf16_f32 v58, v57, s0
	v_ashrrev_i32_e32 v57, 31, v56
	v_lshlrev_b64 v[56:57], 9, v[56:57]
	v_lshl_add_u64 v[56:57], v[60:61], 0, v[56:57]
	global_store_short v[56:57], v58, off
	v_or_b32_e32 v56, 16, v68
	v_lshl_add_u32 v57, v56, 6, v0
	ds_read_b32 v57, v57
	v_or_b32_e32 v56, s40, v56
	s_waitcnt lgkmcnt(0)
	v_fma_f32 v52, v64, v57, v52
	v_mul_f32_e32 v57, 0x3d372713, v52
	v_mul_f32_e32 v57, v52, v57
	v_fma_f32 v57, v52, v57, v52
	v_mul_f32_e32 v57, 0x3f4c422a, v57
	v_mul_f32_e32 v57, 0x4038aa3b, v57
	v_exp_f32_e32 v57, v57
	v_mul_f32_e32 v52, 0.5, v52
	v_add_f32_e32 v57, 1.0, v57
	v_rcp_f32_e32 v57, v57
	s_nop 0
	v_fma_f32 v57, v57, -2.0, 1.0
	v_add_f32_e32 v57, 1.0, v57
	v_mul_f32_e32 v52, v52, v57
	v_ashrrev_i32_e32 v57, 31, v56
	v_lshlrev_b64 v[56:57], 9, v[56:57]
	v_cvt_pk_bf16_f32 v52, v52, s0
	v_lshl_add_u64 v[56:57], v[60:61], 0, v[56:57]
	global_store_short v[56:57], v52, off
	v_or_b32_e32 v52, 17, v68
	v_lshl_add_u32 v56, v52, 6, v0
	ds_read_b32 v56, v56
	v_or_b32_e32 v52, s40, v52
	s_waitcnt lgkmcnt(0)
	v_fma_f32 v53, v64, v56, v53
	v_mul_f32_e32 v56, 0x3d372713, v53
	v_mul_f32_e32 v56, v53, v56
	v_fma_f32 v56, v53, v56, v53
	v_mul_f32_e32 v56, 0x3f4c422a, v56
	v_mul_f32_e32 v56, 0x4038aa3b, v56
	v_exp_f32_e32 v56, v56
	v_mul_f32_e32 v53, 0.5, v53
	v_add_f32_e32 v56, 1.0, v56
	v_rcp_f32_e32 v56, v56
	s_nop 0
	v_fma_f32 v56, v56, -2.0, 1.0
	v_add_f32_e32 v56, 1.0, v56
	v_mul_f32_e32 v53, v53, v56
	v_cvt_pk_bf16_f32 v56, v53, s0
	v_ashrrev_i32_e32 v53, 31, v52
	v_lshlrev_b64 v[52:53], 9, v[52:53]
	v_lshl_add_u64 v[52:53], v[60:61], 0, v[52:53]
	global_store_short v[52:53], v56, off
	v_or_b32_e32 v52, 18, v68
	v_lshl_add_u32 v53, v52, 6, v0
	ds_read_b32 v53, v53
	v_or_b32_e32 v52, s40, v52
	s_waitcnt lgkmcnt(0)
	v_fma_f32 v53, v64, v53, v54
	v_mul_f32_e32 v54, 0x3d372713, v53
	v_mul_f32_e32 v54, v53, v54
	v_fma_f32 v54, v53, v54, v53
	v_mul_f32_e32 v54, 0x3f4c422a, v54
	v_mul_f32_e32 v54, 0x4038aa3b, v54
	v_exp_f32_e32 v54, v54
	v_mul_f32_e32 v53, 0.5, v53
	v_add_f32_e32 v54, 1.0, v54
	v_rcp_f32_e32 v54, v54
	s_nop 0
	v_fma_f32 v54, v54, -2.0, 1.0
	v_add_f32_e32 v54, 1.0, v54
	v_mul_f32_e32 v53, v53, v54
	v_cvt_pk_bf16_f32 v54, v53, s0
	v_ashrrev_i32_e32 v53, 31, v52
	v_lshlrev_b64 v[52:53], 9, v[52:53]
	v_lshl_add_u64 v[52:53], v[60:61], 0, v[52:53]
	global_store_short v[52:53], v54, off
	v_or_b32_e32 v52, 19, v68
	v_lshl_add_u32 v53, v52, 6, v0
	ds_read_b32 v53, v53
	v_or_b32_e32 v52, s40, v52
	s_waitcnt lgkmcnt(0)
	v_fmac_f32_e32 v55, v64, v53
	v_mul_f32_e32 v53, 0x3d372713, v55
	v_mul_f32_e32 v53, v55, v53
	v_fma_f32 v53, v55, v53, v55
	v_mul_f32_e32 v53, 0x3f4c422a, v53
	v_mul_f32_e32 v53, 0x4038aa3b, v53
	v_exp_f32_e32 v53, v53
	v_mul_f32_e32 v54, 0.5, v55
	v_add_f32_e32 v53, 1.0, v53
	v_rcp_f32_e32 v53, v53
	s_nop 0
	v_fma_f32 v53, v53, -2.0, 1.0
	v_add_f32_e32 v53, 1.0, v53
	v_mul_f32_e32 v53, v54, v53
	v_cvt_pk_bf16_f32 v54, v53, s0
	v_ashrrev_i32_e32 v53, 31, v52
	v_lshlrev_b64 v[52:53], 9, v[52:53]
	v_lshl_add_u64 v[52:53], v[60:61], 0, v[52:53]
	global_store_short v[52:53], v54, off
	s_cbranch_vccz .LBB0_716
	s_add_i32 s38, s38, s53
	s_cmpk_gt_i32 s38, 0x3ff
	s_cbranch_scc0 .LBB0_706
	s_cmp_eq_u32 m0, 1
	s_cbranch_scc0 .LBB0_720
	s_mov_b32 m0, 2
	s_waitcnt lgkmcnt(0)
	s_barrier
	s_branch .LBB0_400
